# MoBA softmax half-exchange via v_permlane32_swap instead of ds_bpermute (8 sites)
# speedup vs baseline: 1.0061x; 1.0061x over previous
; __device__ __forceinline__ void moba_item(const Params& p, LAS unsigned char* lds, int b, int h, int qb, int half) {
;     ...
;         tmax = fmaxf(tmax, __shfl_xor(tmax, 32)) * SC;
;         const float m_new = fmaxf(m_run, tmax);
;         const float alpha = __builtin_amdgcn_exp2f(m_run - m_new);
;         const float msub = sel ? m_new : INFINITY;
;         float psum = 0.f;
; #pragma unroll
;         for (int kt = 0; kt < 2; ++kt)
; #pragma unroll
;             for (int i = 0; i < 16; ++i) { const float pv = __builtin_amdgcn_exp2f(__builtin_fmaf(s[kt][i], SC, -msub)); s[kt][i] = pv; psum += pv; }
;         psum += __shfl_xor(psum, 32);
;         l_run = l_run * alpha + psum; m_run = m_new;
.LBB0_452:
	v_and_b32_e32 v164, 64, v238
	v_xor_b32_e32 v161, 32, v238
	v_add_u32_e32 v164, 64, v164
	v_cmp_lt_i32_e32 vcc, v161, v164
	v_max_f32_e32 v184, v183, v183
	s_or_b64 s[0:1], s[0:1], s[6:7]
	v_cndmask_b32_e32 v161, v238, v161, vcc
	v_lshlrev_b32_e32 v161, 2, v161
	v_mov_b32_e32 v182, v181
	v_mov_b32_e32 v161, v181
	s_nop 1
	v_permlane32_swap_b32_e32 v182, v161
	v_max_f32_e32 v181, v181, v181
	v_add_u32_e32 v231, s28, v179
	s_waitcnt lgkmcnt(0)
	v_max_f32_e32 v182, v182, v182
	v_max3_f32 v181, v181, v182, v161
	v_mul_f32_e32 v181, 0x3e0293ee, v181
	v_max_f32_e32 v182, v184, v181
	v_cndmask_b32_e64 v181, v240, -v182, s[0:1]
	v_fmamk_f32 v80, v80, 0x3e0293ee, v181
	v_exp_f32_e32 v188, v80
	v_fmamk_f32 v81, v81, 0x3e0293ee, v181
	v_exp_f32_e32 v189, v81
	v_fmamk_f32 v81, v82, 0x3e0293ee, v181
	v_exp_f32_e32 v190, v81
	v_fmamk_f32 v81, v83, 0x3e0293ee, v181
	v_exp_f32_e32 v191, v81
	v_fmamk_f32 v81, v84, 0x3e0293ee, v181
	v_sub_f32_e32 v80, v183, v182
	v_add_f32_e32 v183, 0, v188
	v_exp_f32_e32 v192, v81
	v_fmamk_f32 v82, v85, 0x3e0293ee, v181
	v_add_f32_e32 v81, v189, v183
	v_exp_f32_e32 v183, v82
	v_fmamk_f32 v82, v86, 0x3e0293ee, v181
	v_add_f32_e32 v81, v190, v81
	v_exp_f32_e32 v194, v82
	v_fmamk_f32 v82, v87, 0x3e0293ee, v181
	v_add_f32_e32 v81, v191, v81
	v_exp_f32_e32 v195, v82
	v_fmamk_f32 v82, v88, 0x3e0293ee, v181
	v_add_f32_e32 v81, v192, v81
	v_exp_f32_e32 v196, v82
	v_fmamk_f32 v82, v89, 0x3e0293ee, v181
	v_add_f32_e32 v81, v183, v81
	v_exp_f32_e32 v197, v82
	v_fmamk_f32 v82, v90, 0x3e0293ee, v181
	v_add_f32_e32 v81, v194, v81
	v_exp_f32_e32 v198, v82
	v_fmamk_f32 v82, v91, 0x3e0293ee, v181
	v_add_f32_e32 v81, v195, v81
	v_exp_f32_e32 v199, v82
	v_fmamk_f32 v82, v92, 0x3e0293ee, v181
	v_add_f32_e32 v81, v196, v81
	v_exp_f32_e32 v202, v82
	v_fmamk_f32 v82, v93, 0x3e0293ee, v181
	v_add_f32_e32 v81, v197, v81
	v_exp_f32_e32 v203, v82
	v_fmamk_f32 v82, v94, 0x3e0293ee, v181
	v_add_f32_e32 v81, v198, v81
	v_exp_f32_e32 v94, v82
	v_fmamk_f32 v82, v95, 0x3e0293ee, v181
	v_add_f32_e32 v81, v199, v81
	v_exp_f32_e32 v95, v82
	v_fmamk_f32 v64, v64, 0x3e0293ee, v181
	v_add_f32_e32 v81, v202, v81
	v_exp_f32_e32 v216, v64
	v_fmamk_f32 v65, v65, 0x3e0293ee, v181
	v_add_f32_e32 v64, v203, v81
	v_exp_f32_e32 v65, v65
	v_fmamk_f32 v66, v66, 0x3e0293ee, v181
	v_add_f32_e32 v64, v94, v64
	v_exp_f32_e32 v217, v66
	v_fmamk_f32 v66, v67, 0x3e0293ee, v181
	v_add_f32_e32 v64, v95, v64
	v_exp_f32_e32 v218, v66
	v_fmamk_f32 v66, v68, 0x3e0293ee, v181
	v_add_f32_e32 v64, v216, v64
	v_exp_f32_e32 v219, v66
	v_fmamk_f32 v66, v69, 0x3e0293ee, v181
	v_add_f32_e32 v64, v65, v64
	v_exp_f32_e32 v220, v66
	v_fmamk_f32 v66, v70, 0x3e0293ee, v181
	v_add_f32_e32 v64, v217, v64
	v_exp_f32_e32 v221, v66
	v_fmamk_f32 v66, v71, 0x3e0293ee, v181
	v_add_f32_e32 v64, v218, v64
	v_exp_f32_e32 v222, v66
	v_fmamk_f32 v66, v72, 0x3e0293ee, v181
	v_add_f32_e32 v64, v219, v64
	v_exp_f32_e32 v223, v66
	v_fmamk_f32 v66, v73, 0x3e0293ee, v181
	v_add_f32_e32 v64, v220, v64
	v_exp_f32_e32 v224, v66
	v_fmamk_f32 v66, v74, 0x3e0293ee, v181
	v_add_f32_e32 v64, v221, v64
	v_exp_f32_e32 v225, v66
	v_fmamk_f32 v66, v75, 0x3e0293ee, v181
	v_add_f32_e32 v64, v222, v64
	v_exp_f32_e32 v226, v66
	v_fmamk_f32 v66, v76, 0x3e0293ee, v181
	v_add_f32_e32 v64, v223, v64
	v_exp_f32_e32 v227, v66
	v_fmamk_f32 v66, v77, 0x3e0293ee, v181
	v_add_f32_e32 v64, v224, v64
	v_exp_f32_e32 v228, v66
	v_fmamk_f32 v66, v78, 0x3e0293ee, v181
	v_add_f32_e32 v64, v225, v64
	v_exp_f32_e32 v229, v66
	v_fmac_f32_e32 v181, 0x3e0293ee, v79
	v_add_f32_e32 v64, v226, v64
	v_exp_f32_e32 v230, v181
	v_add_f32_e32 v64, v227, v64
	v_add_f32_e32 v66, v228, v64
	v_add_f32_e32 v66, v229, v66
	v_add_f32_e32 v66, v230, v66
	v_mov_b32_e32 v67, v66
	v_mov_b32_e32 v161, v66
	s_nop 1
	v_permlane32_swap_b32_e32 v67, v161
	v_exp_f32_e32 v64, v80
	v_cvt_pk_bf16_f32 v188, v188, v189
	v_cvt_pk_bf16_f32 v189, v190, v191
	v_cvt_pk_bf16_f32 v190, v192, v183
	s_waitcnt lgkmcnt(0)
; #define MFMA32(a, b, c) __builtin_amdgcn_mfma_f32_32x32x16_bf16((a), (b), (c), 0, 0, 0)
; __device__ __forceinline__ void moba_item(const Params& p, LAS unsigned char* lds, int b, int h, int qb, int half) {
;     ...
;         l_run = l_run * alpha + psum; m_run = m_new;
;         {
; #pragma unroll
;             for (int dt = 0; dt < 4; ++dt)
; #pragma unroll
;                 for (int i = 0; i < 16; ++i) O[dt][i] *= alpha;
;         }
; #pragma unroll
;         for (int kt = 0; kt < 2; ++kt) {
;             bf16x8 vf0[4], vf1[4];
; #pragma unroll
;             for (int dt = 0; dt < 4; ++dt) {
;                 vf0[dt] = tr_read2(Vl + cb + (64 * team + 32 * kt + 4 * hh + q4) * MB_VS + (32 * dt + 16 * b16 + 4 * p4) * 2, 8 * MB_VS);
;                 vf1[dt] = tr_read2(Vl + cb + (64 * team + 32 * kt + 16 + 4 * hh + q4) * MB_VS + (32 * dt + 16 * b16 + 4 * p4) * 2, 8 * MB_VS);
;             }
;             const bf16x8 pf0 = pack_step<0>(s[kt]), pf1 = pack_step<1>(s[kt]);
;             __builtin_amdgcn_sched_barrier(0);
; #pragma unroll
;             for (int dt = 0; dt < 4; ++dt) O[dt] = MFMA32(vf0[dt], pf0, O[dt]);
; #pragma unroll
;             for (int dt = 0; dt < 4; ++dt) O[dt] = MFMA32(vf1[dt], pf1, O[dt]);
;             __builtin_amdgcn_sched_barrier(0);
;         }
	v_add_f32_e32 v181, v67, v161
	ds_read_b64_tr_b16 v[66:67], v231 offset:34816
	ds_read_b64_tr_b16 v[70:71], v231 offset:34880
	ds_read_b64_tr_b16 v[74:75], v231 offset:34944
	ds_read_b64_tr_b16 v[78:79], v231 offset:35008
	ds_read_b64_tr_b16 v[68:69], v231 offset:37376
	ds_read_b64_tr_b16 v[72:73], v231 offset:37440
	ds_read_b64_tr_b16 v[76:77], v231 offset:37504
	ds_read_b64_tr_b16 v[80:81], v231 offset:37568
	ds_read_b64_tr_b16 v[82:83], v231 offset:39936
	ds_read_b64_tr_b16 v[86:87], v231 offset:40000
	ds_read_b64_tr_b16 v[90:91], v231 offset:40064
	ds_read_b64_tr_b16 v[184:185], v231 offset:40128
	ds_read_b64_tr_b16 v[84:85], v231 offset:42496
	ds_read_b64_tr_b16 v[88:89], v231 offset:42560
	ds_read_b64_tr_b16 v[92:93], v231 offset:42624
	ds_read_b64_tr_b16 v[186:187], v231 offset:42688
	v_pk_mul_f32 v[62:63], v[62:63], v[64:65] op_sel_hi:[1,0]
	v_pk_mul_f32 v[60:61], v[60:61], v[64:65] op_sel_hi:[1,0]
	v_pk_mul_f32 v[58:59], v[58:59], v[64:65] op_sel_hi:[1,0]
	v_pk_mul_f32 v[56:57], v[56:57], v[64:65] op_sel_hi:[1,0]
	v_pk_mul_f32 v[54:55], v[54:55], v[64:65] op_sel_hi:[1,0]
	v_pk_mul_f32 v[52:53], v[52:53], v[64:65] op_sel_hi:[1,0]
	v_pk_mul_f32 v[50:51], v[50:51], v[64:65] op_sel_hi:[1,0]
	v_pk_mul_f32 v[48:49], v[48:49], v[64:65] op_sel_hi:[1,0]
	v_pk_mul_f32 v[46:47], v[46:47], v[64:65] op_sel_hi:[1,0]
	v_pk_mul_f32 v[44:45], v[44:45], v[64:65] op_sel_hi:[1,0]
	v_pk_mul_f32 v[42:43], v[42:43], v[64:65] op_sel_hi:[1,0]
	v_pk_mul_f32 v[40:41], v[40:41], v[64:65] op_sel_hi:[1,0]
	v_pk_mul_f32 v[38:39], v[38:39], v[64:65] op_sel_hi:[1,0]
	v_pk_mul_f32 v[36:37], v[36:37], v[64:65] op_sel_hi:[1,0]
	v_pk_mul_f32 v[34:35], v[34:35], v[64:65] op_sel_hi:[1,0]
	v_pk_mul_f32 v[32:33], v[32:33], v[64:65] op_sel_hi:[1,0]
	v_pk_mul_f32 v[30:31], v[30:31], v[64:65] op_sel_hi:[1,0]
	v_pk_mul_f32 v[28:29], v[28:29], v[64:65] op_sel_hi:[1,0]
	v_pk_mul_f32 v[26:27], v[26:27], v[64:65] op_sel_hi:[1,0]
	v_pk_mul_f32 v[24:25], v[24:25], v[64:65] op_sel_hi:[1,0]
	v_pk_mul_f32 v[22:23], v[22:23], v[64:65] op_sel_hi:[1,0]
	v_pk_mul_f32 v[20:21], v[20:21], v[64:65] op_sel_hi:[1,0]
	v_pk_mul_f32 v[18:19], v[18:19], v[64:65] op_sel_hi:[1,0]
	v_pk_mul_f32 v[16:17], v[16:17], v[64:65] op_sel_hi:[1,0]
	v_pk_mul_f32 v[14:15], v[14:15], v[64:65] op_sel_hi:[1,0]
	v_pk_mul_f32 v[12:13], v[12:13], v[64:65] op_sel_hi:[1,0]
	v_pk_mul_f32 v[10:11], v[10:11], v[64:65] op_sel_hi:[1,0]
	v_pk_mul_f32 v[8:9], v[8:9], v[64:65] op_sel_hi:[1,0]
	v_pk_mul_f32 v[6:7], v[6:7], v[64:65] op_sel_hi:[1,0]
	v_pk_mul_f32 v[4:5], v[4:5], v[64:65] op_sel_hi:[1,0]
	v_pk_mul_f32 v[2:3], v[2:3], v[64:65] op_sel_hi:[1,0]
	v_pk_mul_f32 v[0:1], v[0:1], v[64:65] op_sel_hi:[1,0]
	v_cvt_pk_bf16_f32 v191, v194, v195
	v_cvt_pk_bf16_f32 v194, v196, v197
	v_cvt_pk_bf16_f32 v195, v198, v199
	v_cvt_pk_bf16_f32 v196, v202, v203
	v_cvt_pk_bf16_f32 v197, v94, v95
	s_waitcnt lgkmcnt(11)
	v_mfma_f32_32x32x16_bf16 v[48:63], v[66:69], v[188:191], v[48:63]
	s_waitcnt lgkmcnt(10)
	v_mfma_f32_32x32x16_bf16 v[32:47], v[70:73], v[188:191], v[32:47]
	s_waitcnt lgkmcnt(9)
	v_mfma_f32_32x32x16_bf16 v[16:31], v[74:77], v[188:191], v[16:31]
	s_waitcnt lgkmcnt(8)
	v_mfma_f32_32x32x16_bf16 v[0:15], v[78:81], v[188:191], v[0:15]
	s_waitcnt lgkmcnt(3)
	v_mfma_f32_32x32x16_bf16 v[48:63], v[82:85], v[194:197], v[48:63]
	s_waitcnt lgkmcnt(2)
	v_mfma_f32_32x32x16_bf16 v[32:47], v[86:89], v[194:197], v[32:47]
	s_waitcnt lgkmcnt(1)
	v_mfma_f32_32x32x16_bf16 v[16:31], v[90:93], v[194:197], v[16:31]
	s_waitcnt lgkmcnt(0)
	v_mfma_f32_32x32x16_bf16 v[0:15], v[184:187], v[194:197], v[0:15]
	ds_read_b64_tr_b16 v[66:67], v231 offset:45056
	ds_read_b64_tr_b16 v[70:71], v231 offset:45120
	ds_read_b64_tr_b16 v[74:75], v231 offset:45184
	ds_read_b64_tr_b16 v[78:79], v231 offset:45248
	ds_read_b64_tr_b16 v[68:69], v231 offset:47616
	ds_read_b64_tr_b16 v[72:73], v231 offset:47680
	ds_read_b64_tr_b16 v[76:77], v231 offset:47744
	ds_read_b64_tr_b16 v[80:81], v231 offset:47808
	ds_read_b64_tr_b16 v[82:83], v231 offset:50176
	ds_read_b64_tr_b16 v[86:87], v231 offset:50240
	ds_read_b64_tr_b16 v[90:91], v231 offset:50304
	ds_read_b64_tr_b16 v[184:185], v231 offset:50368
	ds_read_b64_tr_b16 v[84:85], v231 offset:52736
	ds_read_b64_tr_b16 v[88:89], v231 offset:52800
	ds_read_b64_tr_b16 v[92:93], v231 offset:52864
	ds_read_b64_tr_b16 v[186:187], v231 offset:52928
	v_cvt_pk_bf16_f32 v188, v216, v65
	v_cvt_pk_bf16_f32 v189, v217, v218
	v_cvt_pk_bf16_f32 v190, v219, v220
	v_cvt_pk_bf16_f32 v191, v221, v222
	v_cvt_pk_bf16_f32 v194, v223, v224
	v_cvt_pk_bf16_f32 v195, v225, v226
	v_cvt_pk_bf16_f32 v196, v227, v228
	v_cvt_pk_bf16_f32 v197, v229, v230
	s_waitcnt lgkmcnt(11)
	v_mfma_f32_32x32x16_bf16 v[48:63], v[66:69], v[188:191], v[48:63]
	s_waitcnt lgkmcnt(10)
	v_mfma_f32_32x32x16_bf16 v[32:47], v[70:73], v[188:191], v[32:47]
	s_waitcnt lgkmcnt(9)
	v_mfma_f32_32x32x16_bf16 v[16:31], v[74:77], v[188:191], v[16:31]
	s_waitcnt lgkmcnt(8)
	v_mfma_f32_32x32x16_bf16 v[0:15], v[78:81], v[188:191], v[0:15]
	s_waitcnt lgkmcnt(3)
	v_mfma_f32_32x32x16_bf16 v[48:63], v[82:85], v[194:197], v[48:63]
	s_waitcnt lgkmcnt(2)
	v_mfma_f32_32x32x16_bf16 v[32:47], v[86:89], v[194:197], v[32:47]
	s_waitcnt lgkmcnt(1)
	v_mfma_f32_32x32x16_bf16 v[16:31], v[90:93], v[194:197], v[16:31]
	s_waitcnt lgkmcnt(0)
	v_mfma_f32_32x32x16_bf16 v[0:15], v[184:187], v[194:197], v[0:15]
	s_addk_i32 s13, 0x80
	s_add_i32 s27, s27, 1
	s_mov_b64 s[0:1], 0x340000
	v_fmac_f32_e32 v181, v180, v64
	s_cmp_eq_u32 s11, s13
	v_lshl_add_u64 v[162:163], v[162:163], 0, s[0:1]
	s_cbranch_scc1 .LBB0_454
	v_mov_b32_e32 v183, v182
	v_mov_b32_e32 v180, v181
	s_branch .LBB0_446

; #define MFMA32(a, b, c) __builtin_amdgcn_mfma_f32_32x32x16_bf16((a), (b), (c), 0, 0, 0)
; __device__ __forceinline__ void moba_item(const Params& p, LAS unsigned char* lds, int b, int h, int qb, int half) {
;     ...
;         tmax = fmaxf(tmax, __shfl_xor(tmax, 32)) * SC;
;         const float m_new = fmaxf(m_run, tmax);
;         const float alpha = __builtin_amdgcn_exp2f(m_run - m_new);
;         const float msub = sel ? m_new : INFINITY;
;         float psum = 0.f;
; #pragma unroll
;         for (int kt = 0; kt < 2; ++kt)
; #pragma unroll
;             for (int i = 0; i < 16; ++i) { const float pv = __builtin_amdgcn_exp2f(__builtin_fmaf(s[kt][i], SC, -msub)); s[kt][i] = pv; psum += pv; }
;         psum += __shfl_xor(psum, 32);
;         l_run = l_run * alpha + psum; m_run = m_new;
;         {
; #pragma unroll
;             for (int dt = 0; dt < 4; ++dt)
; #pragma unroll
;                 for (int i = 0; i < 16; ++i) O[dt][i] *= alpha;
;         }
; #pragma unroll
;         for (int kt = 0; kt < 2; ++kt) {
;             bf16x8 vf0[4], vf1[4];
; #pragma unroll
;             for (int dt = 0; dt < 4; ++dt) {
;                 vf0[dt] = tr_read2(Vl + cb + (64 * team + 32 * kt + 4 * hh + q4) * MB_VS + (32 * dt + 16 * b16 + 4 * p4) * 2, 8 * MB_VS);
;                 vf1[dt] = tr_read2(Vl + cb + (64 * team + 32 * kt + 16 + 4 * hh + q4) * MB_VS + (32 * dt + 16 * b16 + 4 * p4) * 2, 8 * MB_VS);
;             }
;             const bf16x8 pf0 = pack_step<0>(s[kt]), pf1 = pack_step<1>(s[kt]);
;             __builtin_amdgcn_sched_barrier(0);
; #pragma unroll
;             for (int dt = 0; dt < 4; ++dt) O[dt] = MFMA32(vf0[dt], pf0, O[dt]);
.LBB0_458:
	v_mov_b32_e32 v97, v96
	v_mov_b32_e32 v161, v96
	s_nop 1
	v_permlane32_swap_b32_e32 v97, v161
	v_max_f32_e32 v96, v96, v96
	v_max_f32_e32 v98, v182, v182
	s_or_b64 s[0:1], s[0:1], s[6:7]
	s_waitcnt lgkmcnt(0)
	v_max_f32_e32 v97, v97, v97
	v_max3_f32 v96, v96, v97, v161
	v_mul_f32_e32 v96, 0x3e0293ee, v96
	v_max_f32_e32 v96, v98, v96
	v_cndmask_b32_e64 v98, v240, -v96, s[0:1]
	v_fmamk_f32 v80, v80, 0x3e0293ee, v98
	v_exp_f32_e32 v102, v80
	v_fmamk_f32 v80, v81, 0x3e0293ee, v98
	v_fmamk_f32 v81, v82, 0x3e0293ee, v98
	v_exp_f32_e32 v103, v80
	v_exp_f32_e32 v104, v81
	v_fmamk_f32 v81, v83, 0x3e0293ee, v98
	v_exp_f32_e32 v105, v81
	v_fmamk_f32 v81, v84, 0x3e0293ee, v98
	v_add_f32_e32 v80, 0, v102
	v_exp_f32_e32 v106, v81
	v_fmamk_f32 v81, v85, 0x3e0293ee, v98
	v_add_f32_e32 v80, v103, v80
	v_exp_f32_e32 v107, v81
	v_fmamk_f32 v81, v86, 0x3e0293ee, v98
	v_add_f32_e32 v80, v104, v80
	v_exp_f32_e32 v108, v81
	v_fmamk_f32 v81, v87, 0x3e0293ee, v98
	v_add_f32_e32 v80, v105, v80
	v_exp_f32_e32 v109, v81
	v_fmamk_f32 v81, v88, 0x3e0293ee, v98
	v_add_f32_e32 v80, v106, v80
	v_exp_f32_e32 v110, v81
	v_fmamk_f32 v81, v89, 0x3e0293ee, v98
	v_add_f32_e32 v80, v107, v80
	v_exp_f32_e32 v111, v81
	v_fmamk_f32 v81, v90, 0x3e0293ee, v98
	v_add_f32_e32 v80, v108, v80
	v_exp_f32_e32 v112, v81
	v_fmamk_f32 v81, v91, 0x3e0293ee, v98
	v_add_f32_e32 v80, v109, v80
	v_exp_f32_e32 v113, v81
	v_fmamk_f32 v81, v92, 0x3e0293ee, v98
	v_add_f32_e32 v80, v110, v80
	v_exp_f32_e32 v114, v81
	v_fmamk_f32 v81, v93, 0x3e0293ee, v98
	v_add_f32_e32 v80, v111, v80
	v_exp_f32_e32 v115, v81
	v_fmamk_f32 v81, v94, 0x3e0293ee, v98
	v_add_f32_e32 v80, v112, v80
	v_exp_f32_e32 v94, v81
	v_fmamk_f32 v81, v95, 0x3e0293ee, v98
	v_add_f32_e32 v80, v113, v80
	v_exp_f32_e32 v95, v81
	v_fmamk_f32 v64, v64, 0x3e0293ee, v98
	v_add_f32_e32 v80, v114, v80
	v_exp_f32_e32 v116, v64
	v_fmamk_f32 v65, v65, 0x3e0293ee, v98
	v_add_f32_e32 v64, v115, v80
	v_exp_f32_e32 v65, v65
	v_fmamk_f32 v66, v66, 0x3e0293ee, v98
	v_add_f32_e32 v64, v94, v64
	v_exp_f32_e32 v117, v66
	v_fmamk_f32 v66, v67, 0x3e0293ee, v98
	v_add_f32_e32 v64, v95, v64
	v_exp_f32_e32 v118, v66
	v_fmamk_f32 v66, v68, 0x3e0293ee, v98
	v_add_f32_e32 v64, v116, v64
	v_exp_f32_e32 v119, v66
	v_fmamk_f32 v66, v69, 0x3e0293ee, v98
	v_add_f32_e32 v64, v65, v64
	v_exp_f32_e32 v120, v66
	v_fmamk_f32 v66, v70, 0x3e0293ee, v98
	v_add_f32_e32 v64, v117, v64
	v_exp_f32_e32 v121, v66
	v_fmamk_f32 v66, v71, 0x3e0293ee, v98
	v_add_f32_e32 v64, v118, v64
	v_exp_f32_e32 v122, v66
	v_fmamk_f32 v66, v72, 0x3e0293ee, v98
	v_add_f32_e32 v64, v119, v64
	v_exp_f32_e32 v123, v66
	v_fmamk_f32 v66, v73, 0x3e0293ee, v98
	v_add_f32_e32 v64, v120, v64
	v_exp_f32_e32 v124, v66
	v_fmamk_f32 v66, v74, 0x3e0293ee, v98
	v_add_f32_e32 v64, v121, v64
	v_exp_f32_e32 v125, v66
	v_fmamk_f32 v66, v75, 0x3e0293ee, v98
	v_add_f32_e32 v64, v122, v64
	v_exp_f32_e32 v126, v66
	v_fmamk_f32 v66, v76, 0x3e0293ee, v98
	v_add_f32_e32 v64, v123, v64
	v_exp_f32_e32 v127, v66
	v_fmamk_f32 v66, v77, 0x3e0293ee, v98
	v_add_f32_e32 v64, v124, v64
	v_exp_f32_e32 v128, v66
	v_fmamk_f32 v66, v78, 0x3e0293ee, v98
	v_add_f32_e32 v64, v125, v64
	v_exp_f32_e32 v129, v66
	v_fmac_f32_e32 v98, 0x3e0293ee, v79
	v_add_f32_e32 v64, v126, v64
	v_exp_f32_e32 v130, v98
	v_add_f32_e32 v64, v127, v64
	v_add_f32_e32 v66, v128, v64
	v_add_f32_e32 v66, v129, v66
	v_add_f32_e32 v66, v130, v66
	v_mov_b32_e32 v67, v66
	v_mov_b32_e32 v161, v66
	s_nop 1
	v_permlane32_swap_b32_e32 v67, v161
	s_add_i32 s0, s11, 0
	v_sub_f32_e32 v97, v182, v96
	v_add3_u32 v131, s0, v168, v169
	v_exp_f32_e32 v64, v97
	s_waitcnt lgkmcnt(0)
	v_add_f32_e32 v97, v67, v161
	ds_read_b64_tr_b16 v[66:67], v131 offset:34816
	ds_read_b64_tr_b16 v[70:71], v131 offset:34880
	ds_read_b64_tr_b16 v[74:75], v131 offset:34944
	ds_read_b64_tr_b16 v[78:79], v131 offset:35008
	ds_read_b64_tr_b16 v[68:69], v131 offset:37376
	ds_read_b64_tr_b16 v[72:73], v131 offset:37440
	ds_read_b64_tr_b16 v[76:77], v131 offset:37504
	ds_read_b64_tr_b16 v[80:81], v131 offset:37568
	ds_read_b64_tr_b16 v[82:83], v131 offset:39936
	ds_read_b64_tr_b16 v[86:87], v131 offset:40000
	ds_read_b64_tr_b16 v[90:91], v131 offset:40064
	ds_read_b64_tr_b16 v[98:99], v131 offset:40128
	ds_read_b64_tr_b16 v[84:85], v131 offset:42496
	ds_read_b64_tr_b16 v[88:89], v131 offset:42560
	ds_read_b64_tr_b16 v[92:93], v131 offset:42624
	ds_read_b64_tr_b16 v[100:101], v131 offset:42688
	v_cvt_pk_bf16_f32 v102, v102, v103
	v_pk_mul_f32 v[62:63], v[62:63], v[64:65] op_sel_hi:[1,0]
	v_pk_mul_f32 v[60:61], v[60:61], v[64:65] op_sel_hi:[1,0]
	v_pk_mul_f32 v[58:59], v[58:59], v[64:65] op_sel_hi:[1,0]
	v_pk_mul_f32 v[56:57], v[56:57], v[64:65] op_sel_hi:[1,0]
	v_pk_mul_f32 v[54:55], v[54:55], v[64:65] op_sel_hi:[1,0]
	v_pk_mul_f32 v[52:53], v[52:53], v[64:65] op_sel_hi:[1,0]
	v_pk_mul_f32 v[50:51], v[50:51], v[64:65] op_sel_hi:[1,0]
	v_pk_mul_f32 v[48:49], v[48:49], v[64:65] op_sel_hi:[1,0]
	v_pk_mul_f32 v[46:47], v[46:47], v[64:65] op_sel_hi:[1,0]
	v_pk_mul_f32 v[44:45], v[44:45], v[64:65] op_sel_hi:[1,0]
	v_pk_mul_f32 v[42:43], v[42:43], v[64:65] op_sel_hi:[1,0]
	v_pk_mul_f32 v[40:41], v[40:41], v[64:65] op_sel_hi:[1,0]
	v_pk_mul_f32 v[38:39], v[38:39], v[64:65] op_sel_hi:[1,0]
	v_pk_mul_f32 v[36:37], v[36:37], v[64:65] op_sel_hi:[1,0]
	v_pk_mul_f32 v[34:35], v[34:35], v[64:65] op_sel_hi:[1,0]
	v_pk_mul_f32 v[32:33], v[32:33], v[64:65] op_sel_hi:[1,0]
	v_pk_mul_f32 v[30:31], v[30:31], v[64:65] op_sel_hi:[1,0]
	v_pk_mul_f32 v[28:29], v[28:29], v[64:65] op_sel_hi:[1,0]
	v_pk_mul_f32 v[26:27], v[26:27], v[64:65] op_sel_hi:[1,0]
	v_pk_mul_f32 v[24:25], v[24:25], v[64:65] op_sel_hi:[1,0]
	v_pk_mul_f32 v[22:23], v[22:23], v[64:65] op_sel_hi:[1,0]
	v_pk_mul_f32 v[20:21], v[20:21], v[64:65] op_sel_hi:[1,0]
	v_pk_mul_f32 v[18:19], v[18:19], v[64:65] op_sel_hi:[1,0]
	v_pk_mul_f32 v[16:17], v[16:17], v[64:65] op_sel_hi:[1,0]
	v_pk_mul_f32 v[14:15], v[14:15], v[64:65] op_sel_hi:[1,0]
	v_pk_mul_f32 v[12:13], v[12:13], v[64:65] op_sel_hi:[1,0]
	v_pk_mul_f32 v[10:11], v[10:11], v[64:65] op_sel_hi:[1,0]
	v_pk_mul_f32 v[8:9], v[8:9], v[64:65] op_sel_hi:[1,0]
	v_pk_mul_f32 v[6:7], v[6:7], v[64:65] op_sel_hi:[1,0]
	v_pk_mul_f32 v[4:5], v[4:5], v[64:65] op_sel_hi:[1,0]
	v_pk_mul_f32 v[2:3], v[2:3], v[64:65] op_sel_hi:[1,0]
	v_pk_mul_f32 v[0:1], v[0:1], v[64:65] op_sel_hi:[1,0]
	v_cvt_pk_bf16_f32 v103, v104, v105
	v_cvt_pk_bf16_f32 v104, v106, v107
	v_cvt_pk_bf16_f32 v105, v108, v109
	v_cvt_pk_bf16_f32 v106, v110, v111
	v_cvt_pk_bf16_f32 v107, v112, v113
	v_cvt_pk_bf16_f32 v108, v114, v115
	v_cvt_pk_bf16_f32 v109, v94, v95
	s_waitcnt lgkmcnt(11)
; #define MFMA32(a, b, c) __builtin_amdgcn_mfma_f32_32x32x16_bf16((a), (b), (c), 0, 0, 0)
; __device__ __forceinline__ void moba_item(const Params& p, LAS unsigned char* lds, int b, int h, int qb, int half) {
;     ...
;             for (int dt = 0; dt < 4; ++dt) O[dt] = MFMA32(vf0[dt], pf0, O[dt]);
; #pragma unroll
;             for (int dt = 0; dt < 4; ++dt) O[dt] = MFMA32(vf1[dt], pf1, O[dt]);
;             __builtin_amdgcn_sched_barrier(0);
;         }
;     }
;     ...
;     __syncthreads();
;     if (team == 1) {
; #pragma unroll
;         for (int dt = 0; dt < 4; ++dt)
; #pragma unroll
;             for (int i = 0; i < 16; ++i) OB[((wq * 4 + dt) * 16 + i) * 64 + lane] = O[dt][i];
;         ML[(wq * 64 + lane) * 2] = m_run; ML[(wq * 64 + lane) * 2 + 1] = l_run;
	v_mfma_f32_32x32x16_bf16 v[48:63], v[66:69], v[102:105], v[48:63]
	s_waitcnt lgkmcnt(10)
	v_mfma_f32_32x32x16_bf16 v[32:47], v[70:73], v[102:105], v[32:47]
	s_waitcnt lgkmcnt(9)
	v_mfma_f32_32x32x16_bf16 v[16:31], v[74:77], v[102:105], v[16:31]
	s_waitcnt lgkmcnt(8)
	v_mfma_f32_32x32x16_bf16 v[0:15], v[78:81], v[102:105], v[0:15]
	s_waitcnt lgkmcnt(3)
	v_mfma_f32_32x32x16_bf16 v[48:63], v[82:85], v[106:109], v[48:63]
	s_waitcnt lgkmcnt(2)
	v_mfma_f32_32x32x16_bf16 v[32:47], v[86:89], v[106:109], v[32:47]
	s_waitcnt lgkmcnt(1)
	v_mfma_f32_32x32x16_bf16 v[16:31], v[90:93], v[106:109], v[16:31]
	s_waitcnt lgkmcnt(0)
	v_mfma_f32_32x32x16_bf16 v[0:15], v[98:101], v[106:109], v[0:15]
	ds_read_b64_tr_b16 v[66:67], v131 offset:45056
	ds_read_b64_tr_b16 v[70:71], v131 offset:45120
	ds_read_b64_tr_b16 v[74:75], v131 offset:45184
	ds_read_b64_tr_b16 v[78:79], v131 offset:45248
	ds_read_b64_tr_b16 v[68:69], v131 offset:47616
	ds_read_b64_tr_b16 v[72:73], v131 offset:47680
	ds_read_b64_tr_b16 v[76:77], v131 offset:47744
	ds_read_b64_tr_b16 v[80:81], v131 offset:47808
	ds_read_b64_tr_b16 v[82:83], v131 offset:50176
	ds_read_b64_tr_b16 v[86:87], v131 offset:50240
	ds_read_b64_tr_b16 v[90:91], v131 offset:50304
	ds_read_b64_tr_b16 v[98:99], v131 offset:50368
	ds_read_b64_tr_b16 v[84:85], v131 offset:52736
	ds_read_b64_tr_b16 v[88:89], v131 offset:52800
	ds_read_b64_tr_b16 v[92:93], v131 offset:52864
	ds_read_b64_tr_b16 v[100:101], v131 offset:52928
	v_cvt_pk_bf16_f32 v102, v116, v65
	v_cvt_pk_bf16_f32 v103, v117, v118
	v_cvt_pk_bf16_f32 v104, v119, v120
	v_cvt_pk_bf16_f32 v105, v121, v122
	v_cvt_pk_bf16_f32 v106, v123, v124
	v_cvt_pk_bf16_f32 v107, v125, v126
	v_cvt_pk_bf16_f32 v108, v127, v128
	v_cvt_pk_bf16_f32 v109, v129, v130
	s_waitcnt lgkmcnt(11)
	v_mfma_f32_32x32x16_bf16 v[48:63], v[66:69], v[102:105], v[48:63]
	s_waitcnt lgkmcnt(10)
	v_mfma_f32_32x32x16_bf16 v[32:47], v[70:73], v[102:105], v[32:47]
	s_waitcnt lgkmcnt(9)
	v_mfma_f32_32x32x16_bf16 v[16:31], v[74:77], v[102:105], v[16:31]
	s_waitcnt lgkmcnt(8)
	v_mfma_f32_32x32x16_bf16 v[0:15], v[78:81], v[102:105], v[0:15]
	s_waitcnt lgkmcnt(3)
	v_mfma_f32_32x32x16_bf16 v[48:63], v[82:85], v[106:109], v[48:63]
	s_waitcnt lgkmcnt(2)
	v_mfma_f32_32x32x16_bf16 v[32:47], v[86:89], v[106:109], v[32:47]
	s_waitcnt lgkmcnt(1)
	v_mfma_f32_32x32x16_bf16 v[16:31], v[90:93], v[106:109], v[16:31]
	s_waitcnt lgkmcnt(0)
	v_mfma_f32_32x32x16_bf16 v[0:15], v[98:101], v[106:109], v[0:15]
	v_fmac_f32_e32 v97, v181, v64
	s_cmp_lg_u32 s5, 1
	s_barrier
	s_cbranch_scc1 .LBB0_460
	s_lshl_b32 s0, s4, 14
	s_add_i32 s0, s0, 0
	v_lshl_add_u32 v64, v165, 2, s0
	s_lshl_b32 s0, s4, 9
	s_add_i32 s0, s0, 0
	ds_write2st64_b32 v64, v48, v49 offset1:1
	ds_write2st64_b32 v64, v50, v51 offset0:2 offset1:3
	ds_write2st64_b32 v64, v52, v53 offset0:4 offset1:5
	ds_write2st64_b32 v64, v54, v55 offset0:6 offset1:7
	ds_write2st64_b32 v64, v56, v57 offset0:8 offset1:9
	ds_write2st64_b32 v64, v58, v59 offset0:10 offset1:11
	ds_write2st64_b32 v64, v60, v61 offset0:12 offset1:13
	ds_write2st64_b32 v64, v62, v63 offset0:14 offset1:15
	ds_write2st64_b32 v64, v32, v33 offset0:16 offset1:17
	ds_write2st64_b32 v64, v34, v35 offset0:18 offset1:19
	ds_write2st64_b32 v64, v36, v37 offset0:20 offset1:21
	ds_write2st64_b32 v64, v38, v39 offset0:22 offset1:23
	ds_write2st64_b32 v64, v40, v41 offset0:24 offset1:25
	ds_write2st64_b32 v64, v42, v43 offset0:26 offset1:27
	ds_write2st64_b32 v64, v44, v45 offset0:28 offset1:29
	ds_write2st64_b32 v64, v46, v47 offset0:30 offset1:31
	ds_write2st64_b32 v64, v16, v17 offset0:32 offset1:33
	ds_write2st64_b32 v64, v18, v19 offset0:34 offset1:35
	ds_write2st64_b32 v64, v20, v21 offset0:36 offset1:37
	ds_write2st64_b32 v64, v22, v23 offset0:38 offset1:39
	ds_write2st64_b32 v64, v24, v25 offset0:40 offset1:41
	ds_write2st64_b32 v64, v26, v27 offset0:42 offset1:43
	ds_write2st64_b32 v64, v28, v29 offset0:44 offset1:45
	ds_write2st64_b32 v64, v30, v31 offset0:46 offset1:47
	ds_write2st64_b32 v64, v0, v1 offset0:48 offset1:49
	ds_write2st64_b32 v64, v2, v3 offset0:50 offset1:51
	ds_write2st64_b32 v64, v4, v5 offset0:52 offset1:53
	ds_write2st64_b32 v64, v6, v7 offset0:54 offset1:55
	ds_write2st64_b32 v64, v8, v9 offset0:56 offset1:57
	ds_write2st64_b32 v64, v10, v11 offset0:58 offset1:59
	ds_write2st64_b32 v64, v12, v13 offset0:60 offset1:61
	ds_write2st64_b32 v64, v14, v15 offset0:62 offset1:63
	v_lshl_add_u32 v64, v165, 3, s0
	v_add_u32_e32 v64, 0x10000, v64
	ds_write_b64 v64, v[96:97]

; __device__ __forceinline__ void moba_item(const Params& p, LAS unsigned char* lds, int b, int h, int qb, int half) {
;     ...
;         tmax = fmaxf(tmax, __shfl_xor(tmax, 32)) * SC;
;         const float m_new = fmaxf(m_run, tmax);
;         const float alpha = __builtin_amdgcn_exp2f(m_run - m_new);
;         const float msub = sel ? m_new : INFINITY;
;         float psum = 0.f;
; #pragma unroll
;         for (int kt = 0; kt < 2; ++kt)
; #pragma unroll
;             for (int i = 0; i < 16; ++i) { const float pv = __builtin_amdgcn_exp2f(__builtin_fmaf(s[kt][i], SC, -msub)); s[kt][i] = pv; psum += pv; }
;         psum += __shfl_xor(psum, 32);
;         l_run = l_run * alpha + psum; m_run = m_new;
.LBB0_489:
	v_mov_b32_e32 v188, v187
	v_mov_b32_e32 v161, v187
	s_nop 1
	v_permlane32_swap_b32_e32 v188, v161
	v_max_f32_e32 v187, v187, v187
	v_max_f32_e32 v190, v189, v189
	s_or_b64 s[6:7], s[8:9], s[6:7]
	v_add_u32_e32 v249, s16, v184
	s_waitcnt lgkmcnt(0)
	v_max_f32_e32 v188, v188, v188
	v_max3_f32 v187, v187, v188, v161
	v_mul_f32_e32 v187, 0x3e0293ee, v187
	v_max_f32_e32 v188, v190, v187
	v_sub_f32_e32 v187, v189, v188
	v_cndmask_b32_e64 v189, v240, -v188, s[6:7]
	v_fmamk_f32 v80, v80, 0x3e0293ee, v189
	v_exp_f32_e32 v190, v80
	v_fmamk_f32 v80, v81, 0x3e0293ee, v189
	v_fmamk_f32 v81, v82, 0x3e0293ee, v189
	v_exp_f32_e32 v191, v80
	v_exp_f32_e32 v192, v81
	v_fmamk_f32 v81, v83, 0x3e0293ee, v189
	v_exp_f32_e32 v198, v81
	v_fmamk_f32 v81, v84, 0x3e0293ee, v189
	v_add_f32_e32 v80, 0, v190
	v_exp_f32_e32 v199, v81
	v_fmamk_f32 v81, v85, 0x3e0293ee, v189
	v_add_f32_e32 v80, v191, v80
	v_exp_f32_e32 v202, v81
	v_fmamk_f32 v81, v86, 0x3e0293ee, v189
	v_add_f32_e32 v80, v192, v80
	v_exp_f32_e32 v203, v81
	v_fmamk_f32 v81, v87, 0x3e0293ee, v189
	v_add_f32_e32 v80, v198, v80
	v_exp_f32_e32 v219, v81
	v_fmamk_f32 v81, v88, 0x3e0293ee, v189
	v_add_f32_e32 v80, v199, v80
	v_exp_f32_e32 v220, v81
	v_fmamk_f32 v81, v89, 0x3e0293ee, v189
	v_add_f32_e32 v80, v202, v80
	v_exp_f32_e32 v221, v81
	v_fmamk_f32 v81, v90, 0x3e0293ee, v189
	v_add_f32_e32 v80, v203, v80
	v_exp_f32_e32 v222, v81
	v_fmamk_f32 v81, v91, 0x3e0293ee, v189
	v_add_f32_e32 v80, v219, v80
	v_exp_f32_e32 v223, v81
	v_fmamk_f32 v81, v92, 0x3e0293ee, v189
	v_add_f32_e32 v80, v220, v80
	v_exp_f32_e32 v224, v81
	v_fmamk_f32 v81, v93, 0x3e0293ee, v189
	v_add_f32_e32 v80, v221, v80
	v_exp_f32_e32 v225, v81
	v_fmamk_f32 v81, v94, 0x3e0293ee, v189
	v_add_f32_e32 v80, v222, v80
	v_exp_f32_e32 v94, v81
	v_fmamk_f32 v81, v95, 0x3e0293ee, v189
	v_add_f32_e32 v80, v223, v80
	v_exp_f32_e32 v95, v81
	v_fmamk_f32 v64, v64, 0x3e0293ee, v189
	v_add_f32_e32 v80, v224, v80
	v_exp_f32_e32 v226, v64
	v_fmamk_f32 v65, v65, 0x3e0293ee, v189
	v_add_f32_e32 v64, v225, v80
	v_exp_f32_e32 v65, v65
	v_fmamk_f32 v66, v66, 0x3e0293ee, v189
	v_add_f32_e32 v64, v94, v64
	v_exp_f32_e32 v227, v66
	v_fmamk_f32 v66, v67, 0x3e0293ee, v189
	v_add_f32_e32 v64, v95, v64
	v_exp_f32_e32 v228, v66
	v_fmamk_f32 v66, v68, 0x3e0293ee, v189
	v_add_f32_e32 v64, v226, v64
	v_exp_f32_e32 v229, v66
	v_fmamk_f32 v66, v69, 0x3e0293ee, v189
	v_add_f32_e32 v64, v65, v64
	v_exp_f32_e32 v230, v66
	v_fmamk_f32 v66, v70, 0x3e0293ee, v189
	v_add_f32_e32 v64, v227, v64
	v_exp_f32_e32 v231, v66
	v_fmamk_f32 v66, v71, 0x3e0293ee, v189
	v_add_f32_e32 v64, v228, v64
	v_exp_f32_e32 v232, v66
	v_fmamk_f32 v66, v72, 0x3e0293ee, v189
	v_add_f32_e32 v64, v229, v64
	v_exp_f32_e32 v233, v66
	v_fmamk_f32 v66, v73, 0x3e0293ee, v189
	v_add_f32_e32 v64, v230, v64
	v_exp_f32_e32 v243, v66
	v_fmamk_f32 v66, v74, 0x3e0293ee, v189
	v_add_f32_e32 v64, v231, v64
	v_exp_f32_e32 v244, v66
	v_fmamk_f32 v66, v75, 0x3e0293ee, v189
	v_add_f32_e32 v64, v232, v64
	v_exp_f32_e32 v245, v66
	v_fmamk_f32 v66, v76, 0x3e0293ee, v189
	v_add_f32_e32 v64, v233, v64
	v_exp_f32_e32 v246, v66
	v_fmamk_f32 v66, v77, 0x3e0293ee, v189
	v_add_f32_e32 v64, v243, v64
	v_exp_f32_e32 v247, v66
	v_fmamk_f32 v66, v78, 0x3e0293ee, v189
	v_add_f32_e32 v64, v244, v64
	v_exp_f32_e32 v248, v66
	v_fmac_f32_e32 v189, 0x3e0293ee, v79
	v_add_f32_e32 v64, v245, v64
	v_exp_f32_e32 v189, v189
	v_add_f32_e32 v64, v246, v64
	v_add_f32_e32 v66, v247, v64
	v_add_f32_e32 v66, v248, v66
	v_add_f32_e32 v66, v189, v66
	v_mov_b32_e32 v67, v66
	v_mov_b32_e32 v161, v66
	s_nop 1
	v_permlane32_swap_b32_e32 v67, v161
	v_exp_f32_e32 v64, v187
	v_cvt_pk_bf16_f32 v216, v190, v191
	v_cvt_pk_bf16_f32 v217, v192, v198
	v_cvt_pk_bf16_f32 v218, v199, v202
	s_waitcnt lgkmcnt(0)
; #define MFMA32(a, b, c) __builtin_amdgcn_mfma_f32_32x32x16_bf16((a), (b), (c), 0, 0, 0)
; __device__ __forceinline__ void moba_item(const Params& p, LAS unsigned char* lds, int b, int h, int qb, int half) {
;     ...
;         l_run = l_run * alpha + psum; m_run = m_new;
;         {
; #pragma unroll
;             for (int dt = 0; dt < 4; ++dt)
; #pragma unroll
;                 for (int i = 0; i < 16; ++i) O[dt][i] *= alpha;
;         }
; #pragma unroll
;         for (int kt = 0; kt < 2; ++kt) {
;             bf16x8 vf0[4], vf1[4];
; #pragma unroll
;             for (int dt = 0; dt < 4; ++dt) {
;                 vf0[dt] = tr_read2(Vl + cb + (64 * team + 32 * kt + 4 * hh + q4) * MB_VS + (32 * dt + 16 * b16 + 4 * p4) * 2, 8 * MB_VS);
;                 vf1[dt] = tr_read2(Vl + cb + (64 * team + 32 * kt + 16 + 4 * hh + q4) * MB_VS + (32 * dt + 16 * b16 + 4 * p4) * 2, 8 * MB_VS);
;             }
;             const bf16x8 pf0 = pack_step<0>(s[kt]), pf1 = pack_step<1>(s[kt]);
;             __builtin_amdgcn_sched_barrier(0);
; #pragma unroll
;             for (int dt = 0; dt < 4; ++dt) O[dt] = MFMA32(vf0[dt], pf0, O[dt]);
; #pragma unroll
;             for (int dt = 0; dt < 4; ++dt) O[dt] = MFMA32(vf1[dt], pf1, O[dt]);
;             __builtin_amdgcn_sched_barrier(0);
;         }
	v_add_f32_e32 v187, v67, v161
	ds_read_b64_tr_b16 v[66:67], v249 offset:34816
	ds_read_b64_tr_b16 v[70:71], v249 offset:34880
	ds_read_b64_tr_b16 v[74:75], v249 offset:34944
	ds_read_b64_tr_b16 v[78:79], v249 offset:35008
	ds_read_b64_tr_b16 v[68:69], v249 offset:37376
	ds_read_b64_tr_b16 v[72:73], v249 offset:37440
	ds_read_b64_tr_b16 v[76:77], v249 offset:37504
	ds_read_b64_tr_b16 v[80:81], v249 offset:37568
	ds_read_b64_tr_b16 v[82:83], v249 offset:39936
	ds_read_b64_tr_b16 v[86:87], v249 offset:40000
	ds_read_b64_tr_b16 v[90:91], v249 offset:40064
	ds_read_b64_tr_b16 v[194:195], v249 offset:40128
	ds_read_b64_tr_b16 v[84:85], v249 offset:42496
	ds_read_b64_tr_b16 v[88:89], v249 offset:42560
	ds_read_b64_tr_b16 v[92:93], v249 offset:42624
	ds_read_b64_tr_b16 v[196:197], v249 offset:42688
	v_pk_mul_f32 v[62:63], v[62:63], v[64:65] op_sel_hi:[1,0]
	v_pk_mul_f32 v[60:61], v[60:61], v[64:65] op_sel_hi:[1,0]
	v_pk_mul_f32 v[58:59], v[58:59], v[64:65] op_sel_hi:[1,0]
	v_pk_mul_f32 v[56:57], v[56:57], v[64:65] op_sel_hi:[1,0]
	v_pk_mul_f32 v[54:55], v[54:55], v[64:65] op_sel_hi:[1,0]
	v_pk_mul_f32 v[52:53], v[52:53], v[64:65] op_sel_hi:[1,0]
	v_pk_mul_f32 v[50:51], v[50:51], v[64:65] op_sel_hi:[1,0]
	v_pk_mul_f32 v[48:49], v[48:49], v[64:65] op_sel_hi:[1,0]
	v_pk_mul_f32 v[46:47], v[46:47], v[64:65] op_sel_hi:[1,0]
	v_pk_mul_f32 v[44:45], v[44:45], v[64:65] op_sel_hi:[1,0]
	v_pk_mul_f32 v[42:43], v[42:43], v[64:65] op_sel_hi:[1,0]
	v_pk_mul_f32 v[40:41], v[40:41], v[64:65] op_sel_hi:[1,0]
	v_pk_mul_f32 v[38:39], v[38:39], v[64:65] op_sel_hi:[1,0]
	v_pk_mul_f32 v[36:37], v[36:37], v[64:65] op_sel_hi:[1,0]
	v_pk_mul_f32 v[34:35], v[34:35], v[64:65] op_sel_hi:[1,0]
	v_pk_mul_f32 v[32:33], v[32:33], v[64:65] op_sel_hi:[1,0]
	v_pk_mul_f32 v[30:31], v[30:31], v[64:65] op_sel_hi:[1,0]
	v_pk_mul_f32 v[28:29], v[28:29], v[64:65] op_sel_hi:[1,0]
	v_pk_mul_f32 v[26:27], v[26:27], v[64:65] op_sel_hi:[1,0]
	v_pk_mul_f32 v[24:25], v[24:25], v[64:65] op_sel_hi:[1,0]
	v_pk_mul_f32 v[22:23], v[22:23], v[64:65] op_sel_hi:[1,0]
	v_pk_mul_f32 v[20:21], v[20:21], v[64:65] op_sel_hi:[1,0]
	v_pk_mul_f32 v[18:19], v[18:19], v[64:65] op_sel_hi:[1,0]
	v_pk_mul_f32 v[16:17], v[16:17], v[64:65] op_sel_hi:[1,0]
	v_pk_mul_f32 v[14:15], v[14:15], v[64:65] op_sel_hi:[1,0]
	v_pk_mul_f32 v[12:13], v[12:13], v[64:65] op_sel_hi:[1,0]
	v_pk_mul_f32 v[10:11], v[10:11], v[64:65] op_sel_hi:[1,0]
	v_pk_mul_f32 v[8:9], v[8:9], v[64:65] op_sel_hi:[1,0]
	v_pk_mul_f32 v[6:7], v[6:7], v[64:65] op_sel_hi:[1,0]
	v_pk_mul_f32 v[4:5], v[4:5], v[64:65] op_sel_hi:[1,0]
	v_pk_mul_f32 v[2:3], v[2:3], v[64:65] op_sel_hi:[1,0]
	v_pk_mul_f32 v[0:1], v[0:1], v[64:65] op_sel_hi:[1,0]
	v_cvt_pk_bf16_f32 v219, v203, v219
	v_cvt_pk_bf16_f32 v220, v220, v221
	v_cvt_pk_bf16_f32 v221, v222, v223
	v_cvt_pk_bf16_f32 v222, v224, v225
	v_cvt_pk_bf16_f32 v223, v94, v95
	s_waitcnt lgkmcnt(11)
	v_mfma_f32_32x32x16_bf16 v[48:63], v[66:69], v[216:219], v[48:63]
	s_waitcnt lgkmcnt(10)
	v_mfma_f32_32x32x16_bf16 v[32:47], v[70:73], v[216:219], v[32:47]
	s_waitcnt lgkmcnt(9)
	v_mfma_f32_32x32x16_bf16 v[16:31], v[74:77], v[216:219], v[16:31]
	s_waitcnt lgkmcnt(8)
	v_mfma_f32_32x32x16_bf16 v[0:15], v[78:81], v[216:219], v[0:15]
	s_waitcnt lgkmcnt(3)
	v_mfma_f32_32x32x16_bf16 v[48:63], v[82:85], v[220:223], v[48:63]
	s_waitcnt lgkmcnt(2)
	v_mfma_f32_32x32x16_bf16 v[32:47], v[86:89], v[220:223], v[32:47]
	s_waitcnt lgkmcnt(1)
	v_mfma_f32_32x32x16_bf16 v[16:31], v[90:93], v[220:223], v[16:31]
	s_waitcnt lgkmcnt(0)
	v_mfma_f32_32x32x16_bf16 v[0:15], v[194:197], v[220:223], v[0:15]
	ds_read_b64_tr_b16 v[66:67], v249 offset:45056
	ds_read_b64_tr_b16 v[70:71], v249 offset:45120
	ds_read_b64_tr_b16 v[74:75], v249 offset:45184
	ds_read_b64_tr_b16 v[78:79], v249 offset:45248
	ds_read_b64_tr_b16 v[68:69], v249 offset:47616
	ds_read_b64_tr_b16 v[72:73], v249 offset:47680
	ds_read_b64_tr_b16 v[76:77], v249 offset:47744
	ds_read_b64_tr_b16 v[80:81], v249 offset:47808
	ds_read_b64_tr_b16 v[82:83], v249 offset:50176
	ds_read_b64_tr_b16 v[86:87], v249 offset:50240
	ds_read_b64_tr_b16 v[90:91], v249 offset:50304
	ds_read_b64_tr_b16 v[194:195], v249 offset:50368
	ds_read_b64_tr_b16 v[84:85], v249 offset:52736
	ds_read_b64_tr_b16 v[88:89], v249 offset:52800
	ds_read_b64_tr_b16 v[92:93], v249 offset:52864
	ds_read_b64_tr_b16 v[196:197], v249 offset:52928
	v_cvt_pk_bf16_f32 v216, v226, v65
	v_cvt_pk_bf16_f32 v217, v227, v228
	v_cvt_pk_bf16_f32 v218, v229, v230
	v_cvt_pk_bf16_f32 v219, v231, v232
	v_cvt_pk_bf16_f32 v220, v233, v243
	v_cvt_pk_bf16_f32 v221, v244, v245
	v_cvt_pk_bf16_f32 v222, v246, v247
	v_cvt_pk_bf16_f32 v223, v248, v189
	s_waitcnt lgkmcnt(11)
	v_mfma_f32_32x32x16_bf16 v[48:63], v[66:69], v[216:219], v[48:63]
	s_waitcnt lgkmcnt(10)
	v_mfma_f32_32x32x16_bf16 v[32:47], v[70:73], v[216:219], v[32:47]
	s_waitcnt lgkmcnt(9)
	v_mfma_f32_32x32x16_bf16 v[16:31], v[74:77], v[216:219], v[16:31]
	s_waitcnt lgkmcnt(8)
	v_mfma_f32_32x32x16_bf16 v[0:15], v[78:81], v[216:219], v[0:15]
	s_waitcnt lgkmcnt(3)
	v_mfma_f32_32x32x16_bf16 v[48:63], v[82:85], v[220:223], v[48:63]
	s_waitcnt lgkmcnt(2)
	v_mfma_f32_32x32x16_bf16 v[32:47], v[86:89], v[220:223], v[32:47]
	s_waitcnt lgkmcnt(1)
	v_mfma_f32_32x32x16_bf16 v[16:31], v[90:93], v[220:223], v[16:31]
	s_waitcnt lgkmcnt(0)
	v_mfma_f32_32x32x16_bf16 v[0:15], v[194:197], v[220:223], v[0:15]
	s_add_u32 s0, s0, 0x340000
	s_addc_u32 s1, s1, 0
	s_add_i32 s14, s14, 1
	v_fmac_f32_e32 v187, v186, v64
	s_cmp_eq_u32 s13, s0
	v_add_u32_e32 v185, 0x80, v185
	s_cbranch_scc1 .LBB0_491
	v_mov_b32_e32 v189, v188
	v_mov_b32_e32 v186, v187
	s_branch .LBB0_483

; #define MFMA32(a, b, c) __builtin_amdgcn_mfma_f32_32x32x16_bf16((a), (b), (c), 0, 0, 0)
; __device__ __forceinline__ void moba_item(const Params& p, LAS unsigned char* lds, int b, int h, int qb, int half) {
;     ...
;         tmax = fmaxf(tmax, __shfl_xor(tmax, 32)) * SC;
;         const float m_new = fmaxf(m_run, tmax);
;         const float alpha = __builtin_amdgcn_exp2f(m_run - m_new);
;         const float msub = sel ? m_new : INFINITY;
;         float psum = 0.f;
; #pragma unroll
;         for (int kt = 0; kt < 2; ++kt)
; #pragma unroll
;             for (int i = 0; i < 16; ++i) { const float pv = __builtin_amdgcn_exp2f(__builtin_fmaf(s[kt][i], SC, -msub)); s[kt][i] = pv; psum += pv; }
;         psum += __shfl_xor(psum, 32);
;         l_run = l_run * alpha + psum; m_run = m_new;
;         {
; #pragma unroll
;             for (int dt = 0; dt < 4; ++dt)
; #pragma unroll
;                 for (int i = 0; i < 16; ++i) O[dt][i] *= alpha;
;         }
; #pragma unroll
;         for (int kt = 0; kt < 2; ++kt) {
;             bf16x8 vf0[4], vf1[4];
; #pragma unroll
;             for (int dt = 0; dt < 4; ++dt) {
;                 vf0[dt] = tr_read2(Vl + cb + (64 * team + 32 * kt + 4 * hh + q4) * MB_VS + (32 * dt + 16 * b16 + 4 * p4) * 2, 8 * MB_VS);
;                 vf1[dt] = tr_read2(Vl + cb + (64 * team + 32 * kt + 16 + 4 * hh + q4) * MB_VS + (32 * dt + 16 * b16 + 4 * p4) * 2, 8 * MB_VS);
;             }
;             const bf16x8 pf0 = pack_step<0>(s[kt]), pf1 = pack_step<1>(s[kt]);
;             __builtin_amdgcn_sched_barrier(0);
; #pragma unroll
;             for (int dt = 0; dt < 4; ++dt) O[dt] = MFMA32(vf0[dt], pf0, O[dt]);
.LBB0_495:
	v_mov_b32_e32 v97, v96
	v_mov_b32_e32 v161, v96
	s_nop 1
	v_permlane32_swap_b32_e32 v97, v161
	v_max_f32_e32 v96, v96, v96
	v_max_f32_e32 v98, v188, v188
	s_or_b64 s[0:1], s[0:1], s[6:7]
	s_waitcnt lgkmcnt(0)
	v_max_f32_e32 v97, v97, v97
	v_max3_f32 v96, v96, v97, v161
	v_mul_f32_e32 v96, 0x3e0293ee, v96
	v_max_f32_e32 v96, v98, v96
	v_cndmask_b32_e64 v98, v240, -v96, s[0:1]
	v_fmamk_f32 v80, v80, 0x3e0293ee, v98
	v_exp_f32_e32 v102, v80
	v_fmamk_f32 v80, v81, 0x3e0293ee, v98
	v_fmamk_f32 v81, v82, 0x3e0293ee, v98
	v_exp_f32_e32 v103, v80
	v_exp_f32_e32 v104, v81
	v_fmamk_f32 v81, v83, 0x3e0293ee, v98
	v_exp_f32_e32 v105, v81
	v_fmamk_f32 v81, v84, 0x3e0293ee, v98
	v_add_f32_e32 v80, 0, v102
	v_exp_f32_e32 v106, v81
	v_fmamk_f32 v81, v85, 0x3e0293ee, v98
	v_add_f32_e32 v80, v103, v80
	v_exp_f32_e32 v107, v81
	v_fmamk_f32 v81, v86, 0x3e0293ee, v98
	v_add_f32_e32 v80, v104, v80
	v_exp_f32_e32 v108, v81
	v_fmamk_f32 v81, v87, 0x3e0293ee, v98
	v_add_f32_e32 v80, v105, v80
	v_exp_f32_e32 v109, v81
	v_fmamk_f32 v81, v88, 0x3e0293ee, v98
	v_add_f32_e32 v80, v106, v80
	v_exp_f32_e32 v110, v81
	v_fmamk_f32 v81, v89, 0x3e0293ee, v98
	v_add_f32_e32 v80, v107, v80
	v_exp_f32_e32 v111, v81
	v_fmamk_f32 v81, v90, 0x3e0293ee, v98
	v_add_f32_e32 v80, v108, v80
	v_exp_f32_e32 v112, v81
	v_fmamk_f32 v81, v91, 0x3e0293ee, v98
	v_add_f32_e32 v80, v109, v80
	v_exp_f32_e32 v113, v81
	v_fmamk_f32 v81, v92, 0x3e0293ee, v98
	v_add_f32_e32 v80, v110, v80
	v_exp_f32_e32 v114, v81
	v_fmamk_f32 v81, v93, 0x3e0293ee, v98
	v_add_f32_e32 v80, v111, v80
	v_exp_f32_e32 v115, v81
	v_fmamk_f32 v81, v94, 0x3e0293ee, v98
	v_add_f32_e32 v80, v112, v80
	v_exp_f32_e32 v94, v81
	v_fmamk_f32 v81, v95, 0x3e0293ee, v98
	v_add_f32_e32 v80, v113, v80
	v_exp_f32_e32 v95, v81
	v_fmamk_f32 v64, v64, 0x3e0293ee, v98
	v_add_f32_e32 v80, v114, v80
	v_exp_f32_e32 v116, v64
	v_fmamk_f32 v65, v65, 0x3e0293ee, v98
	v_add_f32_e32 v64, v115, v80
	v_exp_f32_e32 v65, v65
	v_fmamk_f32 v66, v66, 0x3e0293ee, v98
	v_add_f32_e32 v64, v94, v64
	v_exp_f32_e32 v117, v66
	v_fmamk_f32 v66, v67, 0x3e0293ee, v98
	v_add_f32_e32 v64, v95, v64
	v_exp_f32_e32 v118, v66
	v_fmamk_f32 v66, v68, 0x3e0293ee, v98
	v_add_f32_e32 v64, v116, v64
	v_exp_f32_e32 v119, v66
	v_fmamk_f32 v66, v69, 0x3e0293ee, v98
	v_add_f32_e32 v64, v65, v64
	v_exp_f32_e32 v120, v66
	v_fmamk_f32 v66, v70, 0x3e0293ee, v98
	v_add_f32_e32 v64, v117, v64
	v_exp_f32_e32 v121, v66
	v_fmamk_f32 v66, v71, 0x3e0293ee, v98
	v_add_f32_e32 v64, v118, v64
	v_exp_f32_e32 v122, v66
	v_fmamk_f32 v66, v72, 0x3e0293ee, v98
	v_add_f32_e32 v64, v119, v64
	v_exp_f32_e32 v123, v66
	v_fmamk_f32 v66, v73, 0x3e0293ee, v98
	v_add_f32_e32 v64, v120, v64
	v_exp_f32_e32 v124, v66
	v_fmamk_f32 v66, v74, 0x3e0293ee, v98
	v_add_f32_e32 v64, v121, v64
	v_exp_f32_e32 v125, v66
	v_fmamk_f32 v66, v75, 0x3e0293ee, v98
	v_add_f32_e32 v64, v122, v64
	v_exp_f32_e32 v126, v66
	v_fmamk_f32 v66, v76, 0x3e0293ee, v98
	v_add_f32_e32 v64, v123, v64
	v_exp_f32_e32 v127, v66
	v_fmamk_f32 v66, v77, 0x3e0293ee, v98
	v_add_f32_e32 v64, v124, v64
	v_exp_f32_e32 v128, v66
	v_fmamk_f32 v66, v78, 0x3e0293ee, v98
	v_add_f32_e32 v64, v125, v64
	v_exp_f32_e32 v129, v66
	v_fmac_f32_e32 v98, 0x3e0293ee, v79
	v_add_f32_e32 v64, v126, v64
	v_exp_f32_e32 v130, v98
	v_add_f32_e32 v64, v127, v64
	v_add_f32_e32 v66, v128, v64
	v_add_f32_e32 v66, v129, v66
	v_add_f32_e32 v66, v130, v66
	v_mov_b32_e32 v67, v66
	v_mov_b32_e32 v161, v66
	s_nop 1
	v_permlane32_swap_b32_e32 v67, v161
	s_add_i32 s0, s10, 0
	v_sub_f32_e32 v97, v188, v96
	v_add3_u32 v131, s0, v166, v167
	v_exp_f32_e32 v64, v97
	s_waitcnt lgkmcnt(0)
	v_add_f32_e32 v97, v67, v161
	ds_read_b64_tr_b16 v[66:67], v131 offset:34816
	ds_read_b64_tr_b16 v[70:71], v131 offset:34880
	ds_read_b64_tr_b16 v[74:75], v131 offset:34944
	ds_read_b64_tr_b16 v[78:79], v131 offset:35008
	ds_read_b64_tr_b16 v[68:69], v131 offset:37376
	ds_read_b64_tr_b16 v[72:73], v131 offset:37440
	ds_read_b64_tr_b16 v[76:77], v131 offset:37504
	ds_read_b64_tr_b16 v[80:81], v131 offset:37568
	ds_read_b64_tr_b16 v[82:83], v131 offset:39936
	ds_read_b64_tr_b16 v[86:87], v131 offset:40000
	ds_read_b64_tr_b16 v[90:91], v131 offset:40064
	ds_read_b64_tr_b16 v[98:99], v131 offset:40128
	ds_read_b64_tr_b16 v[84:85], v131 offset:42496
	ds_read_b64_tr_b16 v[88:89], v131 offset:42560
	ds_read_b64_tr_b16 v[92:93], v131 offset:42624
	ds_read_b64_tr_b16 v[100:101], v131 offset:42688
	v_cvt_pk_bf16_f32 v102, v102, v103
	v_pk_mul_f32 v[62:63], v[62:63], v[64:65] op_sel_hi:[1,0]
	v_pk_mul_f32 v[60:61], v[60:61], v[64:65] op_sel_hi:[1,0]
	v_pk_mul_f32 v[58:59], v[58:59], v[64:65] op_sel_hi:[1,0]
	v_pk_mul_f32 v[56:57], v[56:57], v[64:65] op_sel_hi:[1,0]
	v_pk_mul_f32 v[54:55], v[54:55], v[64:65] op_sel_hi:[1,0]
	v_pk_mul_f32 v[52:53], v[52:53], v[64:65] op_sel_hi:[1,0]
	v_pk_mul_f32 v[50:51], v[50:51], v[64:65] op_sel_hi:[1,0]
	v_pk_mul_f32 v[48:49], v[48:49], v[64:65] op_sel_hi:[1,0]
	v_pk_mul_f32 v[46:47], v[46:47], v[64:65] op_sel_hi:[1,0]
	v_pk_mul_f32 v[44:45], v[44:45], v[64:65] op_sel_hi:[1,0]
	v_pk_mul_f32 v[42:43], v[42:43], v[64:65] op_sel_hi:[1,0]
	v_pk_mul_f32 v[40:41], v[40:41], v[64:65] op_sel_hi:[1,0]
	v_pk_mul_f32 v[38:39], v[38:39], v[64:65] op_sel_hi:[1,0]
	v_pk_mul_f32 v[36:37], v[36:37], v[64:65] op_sel_hi:[1,0]
	v_pk_mul_f32 v[34:35], v[34:35], v[64:65] op_sel_hi:[1,0]
	v_pk_mul_f32 v[32:33], v[32:33], v[64:65] op_sel_hi:[1,0]
	v_pk_mul_f32 v[30:31], v[30:31], v[64:65] op_sel_hi:[1,0]
	v_pk_mul_f32 v[28:29], v[28:29], v[64:65] op_sel_hi:[1,0]
	v_pk_mul_f32 v[26:27], v[26:27], v[64:65] op_sel_hi:[1,0]
	v_pk_mul_f32 v[24:25], v[24:25], v[64:65] op_sel_hi:[1,0]
	v_pk_mul_f32 v[22:23], v[22:23], v[64:65] op_sel_hi:[1,0]
	v_pk_mul_f32 v[20:21], v[20:21], v[64:65] op_sel_hi:[1,0]
	v_pk_mul_f32 v[18:19], v[18:19], v[64:65] op_sel_hi:[1,0]
	v_pk_mul_f32 v[16:17], v[16:17], v[64:65] op_sel_hi:[1,0]
	v_pk_mul_f32 v[14:15], v[14:15], v[64:65] op_sel_hi:[1,0]
	v_pk_mul_f32 v[12:13], v[12:13], v[64:65] op_sel_hi:[1,0]
	v_pk_mul_f32 v[10:11], v[10:11], v[64:65] op_sel_hi:[1,0]
	v_pk_mul_f32 v[8:9], v[8:9], v[64:65] op_sel_hi:[1,0]
	v_pk_mul_f32 v[6:7], v[6:7], v[64:65] op_sel_hi:[1,0]
	v_pk_mul_f32 v[4:5], v[4:5], v[64:65] op_sel_hi:[1,0]
	v_pk_mul_f32 v[2:3], v[2:3], v[64:65] op_sel_hi:[1,0]
	v_pk_mul_f32 v[0:1], v[0:1], v[64:65] op_sel_hi:[1,0]
	v_cvt_pk_bf16_f32 v103, v104, v105
	v_cvt_pk_bf16_f32 v104, v106, v107
	v_cvt_pk_bf16_f32 v105, v108, v109
	v_cvt_pk_bf16_f32 v106, v110, v111
	v_cvt_pk_bf16_f32 v107, v112, v113
	v_cvt_pk_bf16_f32 v108, v114, v115
	v_cvt_pk_bf16_f32 v109, v94, v95
	s_waitcnt lgkmcnt(11)
; #define MFMA32(a, b, c) __builtin_amdgcn_mfma_f32_32x32x16_bf16((a), (b), (c), 0, 0, 0)
; __device__ __forceinline__ void moba_item(const Params& p, LAS unsigned char* lds, int b, int h, int qb, int half) {
;     ...
;             for (int dt = 0; dt < 4; ++dt) O[dt] = MFMA32(vf0[dt], pf0, O[dt]);
; #pragma unroll
;             for (int dt = 0; dt < 4; ++dt) O[dt] = MFMA32(vf1[dt], pf1, O[dt]);
;             __builtin_amdgcn_sched_barrier(0);
;         }
;     }
;     ...
;     __syncthreads();
;     if (team == 1) {
; #pragma unroll
;         for (int dt = 0; dt < 4; ++dt)
; #pragma unroll
;             for (int i = 0; i < 16; ++i) OB[((wq * 4 + dt) * 16 + i) * 64 + lane] = O[dt][i];
;         ML[(wq * 64 + lane) * 2] = m_run; ML[(wq * 64 + lane) * 2 + 1] = l_run;
	v_mfma_f32_32x32x16_bf16 v[48:63], v[66:69], v[102:105], v[48:63]
	s_waitcnt lgkmcnt(10)
	v_mfma_f32_32x32x16_bf16 v[32:47], v[70:73], v[102:105], v[32:47]
	s_waitcnt lgkmcnt(9)
	v_mfma_f32_32x32x16_bf16 v[16:31], v[74:77], v[102:105], v[16:31]
	s_waitcnt lgkmcnt(8)
	v_mfma_f32_32x32x16_bf16 v[0:15], v[78:81], v[102:105], v[0:15]
	s_waitcnt lgkmcnt(3)
	v_mfma_f32_32x32x16_bf16 v[48:63], v[82:85], v[106:109], v[48:63]
	s_waitcnt lgkmcnt(2)
	v_mfma_f32_32x32x16_bf16 v[32:47], v[86:89], v[106:109], v[32:47]
	s_waitcnt lgkmcnt(1)
	v_mfma_f32_32x32x16_bf16 v[16:31], v[90:93], v[106:109], v[16:31]
	s_waitcnt lgkmcnt(0)
	v_mfma_f32_32x32x16_bf16 v[0:15], v[98:101], v[106:109], v[0:15]
	ds_read_b64_tr_b16 v[66:67], v131 offset:45056
	ds_read_b64_tr_b16 v[70:71], v131 offset:45120
	ds_read_b64_tr_b16 v[74:75], v131 offset:45184
	ds_read_b64_tr_b16 v[78:79], v131 offset:45248
	ds_read_b64_tr_b16 v[68:69], v131 offset:47616
	ds_read_b64_tr_b16 v[72:73], v131 offset:47680
	ds_read_b64_tr_b16 v[76:77], v131 offset:47744
	ds_read_b64_tr_b16 v[80:81], v131 offset:47808
	ds_read_b64_tr_b16 v[82:83], v131 offset:50176
	ds_read_b64_tr_b16 v[86:87], v131 offset:50240
	ds_read_b64_tr_b16 v[90:91], v131 offset:50304
	ds_read_b64_tr_b16 v[98:99], v131 offset:50368
	ds_read_b64_tr_b16 v[84:85], v131 offset:52736
	ds_read_b64_tr_b16 v[88:89], v131 offset:52800
	ds_read_b64_tr_b16 v[92:93], v131 offset:52864
	ds_read_b64_tr_b16 v[100:101], v131 offset:52928
	v_cvt_pk_bf16_f32 v102, v116, v65
	v_cvt_pk_bf16_f32 v103, v117, v118
	v_cvt_pk_bf16_f32 v104, v119, v120
	v_cvt_pk_bf16_f32 v105, v121, v122
	v_cvt_pk_bf16_f32 v106, v123, v124
	v_cvt_pk_bf16_f32 v107, v125, v126
	v_cvt_pk_bf16_f32 v108, v127, v128
	v_cvt_pk_bf16_f32 v109, v129, v130
	s_waitcnt lgkmcnt(11)
	v_mfma_f32_32x32x16_bf16 v[48:63], v[66:69], v[102:105], v[48:63]
	s_waitcnt lgkmcnt(10)
	v_mfma_f32_32x32x16_bf16 v[32:47], v[70:73], v[102:105], v[32:47]
	s_waitcnt lgkmcnt(9)
	v_mfma_f32_32x32x16_bf16 v[16:31], v[74:77], v[102:105], v[16:31]
	s_waitcnt lgkmcnt(8)
	v_mfma_f32_32x32x16_bf16 v[0:15], v[78:81], v[102:105], v[0:15]
	s_waitcnt lgkmcnt(3)
	v_mfma_f32_32x32x16_bf16 v[48:63], v[82:85], v[106:109], v[48:63]
	s_waitcnt lgkmcnt(2)
	v_mfma_f32_32x32x16_bf16 v[32:47], v[86:89], v[106:109], v[32:47]
	s_waitcnt lgkmcnt(1)
	v_mfma_f32_32x32x16_bf16 v[16:31], v[90:93], v[106:109], v[16:31]
	s_waitcnt lgkmcnt(0)
	v_mfma_f32_32x32x16_bf16 v[0:15], v[98:101], v[106:109], v[0:15]
	v_fmac_f32_e32 v97, v187, v64
	s_cmp_lg_u32 s5, 1
	s_barrier
	s_cbranch_scc1 .LBB0_497
	s_lshl_b32 s0, s4, 14
	s_add_i32 s0, s0, 0
	v_lshl_add_u32 v64, v165, 2, s0
	s_lshl_b32 s0, s4, 9
	s_add_i32 s0, s0, 0
	ds_write2st64_b32 v64, v48, v49 offset1:1
	ds_write2st64_b32 v64, v50, v51 offset0:2 offset1:3
	ds_write2st64_b32 v64, v52, v53 offset0:4 offset1:5
	ds_write2st64_b32 v64, v54, v55 offset0:6 offset1:7
	ds_write2st64_b32 v64, v56, v57 offset0:8 offset1:9
	ds_write2st64_b32 v64, v58, v59 offset0:10 offset1:11
	ds_write2st64_b32 v64, v60, v61 offset0:12 offset1:13
	ds_write2st64_b32 v64, v62, v63 offset0:14 offset1:15
	ds_write2st64_b32 v64, v32, v33 offset0:16 offset1:17
	ds_write2st64_b32 v64, v34, v35 offset0:18 offset1:19
	ds_write2st64_b32 v64, v36, v37 offset0:20 offset1:21
	ds_write2st64_b32 v64, v38, v39 offset0:22 offset1:23
	ds_write2st64_b32 v64, v40, v41 offset0:24 offset1:25
	ds_write2st64_b32 v64, v42, v43 offset0:26 offset1:27
	ds_write2st64_b32 v64, v44, v45 offset0:28 offset1:29
	ds_write2st64_b32 v64, v46, v47 offset0:30 offset1:31
	ds_write2st64_b32 v64, v16, v17 offset0:32 offset1:33
	ds_write2st64_b32 v64, v18, v19 offset0:34 offset1:35
	ds_write2st64_b32 v64, v20, v21 offset0:36 offset1:37
	ds_write2st64_b32 v64, v22, v23 offset0:38 offset1:39
	ds_write2st64_b32 v64, v24, v25 offset0:40 offset1:41
	ds_write2st64_b32 v64, v26, v27 offset0:42 offset1:43
	ds_write2st64_b32 v64, v28, v29 offset0:44 offset1:45
	ds_write2st64_b32 v64, v30, v31 offset0:46 offset1:47
	ds_write2st64_b32 v64, v0, v1 offset0:48 offset1:49
	ds_write2st64_b32 v64, v2, v3 offset0:50 offset1:51
	ds_write2st64_b32 v64, v4, v5 offset0:52 offset1:53
	ds_write2st64_b32 v64, v6, v7 offset0:54 offset1:55
	ds_write2st64_b32 v64, v8, v9 offset0:56 offset1:57
	ds_write2st64_b32 v64, v10, v11 offset0:58 offset1:59
	ds_write2st64_b32 v64, v12, v13 offset0:60 offset1:61
	ds_write2st64_b32 v64, v14, v15 offset0:62 offset1:63
	v_lshl_add_u32 v64, v165, 3, s0
	v_add_u32_e32 v64, 0x10000, v64
	ds_write_b64 v64, v[96:97]
